# NSA selected loop masked path hand-scheduled: mask compares first, QK(hh1) overlapped with softmax(hh0), PV(hh0) with softmax(hh1)
# speedup vs baseline: 1.0058x; 1.0058x over previous
; template <int MODE, bool FX>
; DI void attn_compute(const int lane, const bf16_t* Ks, const bf16_t* Vs, const bf16x8 (&qf)[2][2], AttnSt& st, const float (&invl)[2],
;                      int lo, int hi, float (&impA)[4], float (&impE)[4], const float CL) {
;     ...
;   for (int ks = 0; ks < 2; ++ks) {
; #pragma unroll
;     for (int kt = 0; kt < 4; ++kt) {
;       int row = kt * 16 + col;
;       bf16x8 kf = *(const bf16x8*)(Ks + row * 64 + (((ks * 4 + quad) ^ ((row >> 1) & 7)) << 3));
; #pragma unroll
;       for (int hh = 0; hh < 2; ++hh) S[kt][hh] = mfma16(kf, qf[hh][ks], S[kt][hh]);
;     }
;   }
;   bf16x8 pf[2][2];
;   const bool full = (lo <= 0) && (hi >= 63);
;   const bool none = (hi < 0) || (lo > 63) || (hi < lo);
;   if (__all(full || none)) {
;     constexpr float L2E = 1.4426950408889634f;
; #pragma unroll
;     for (int hh = 0; hh < 2; ++hh) {
;       float mL;
;       float il = 1.f;
;       if (FX) {
;         mL = full ? CL : 1e30f;
;         if (MODE == 1) il = invl[hh];
;       } else if (MODE != 1) {
;         float mx = -1e30f;
; #pragma unroll
;         for (int kt = 0; kt < 4; ++kt)
; #pragma unroll
;           for (int j = 0; j < 4; ++j) mx = fmaxf(mx, S[kt][hh][j]);
;         mx = full ? mx : -1e30f;
;         mx = fmaxf(mx, shx(mx, 16, lane));
;         mx = fmaxf(mx, shx(mx, 32, lane));
;         const float m_new = fmaxf(st.m[hh], mx);
;         const float alpha = __expf(st.m[hh] - m_new);
;         st.m[hh] = m_new;
;         st.l[hh] *= alpha;
;         if (MODE == 2) {
; #pragma unroll
;           for (int dt = 0; dt < 4; ++dt) st.O[hh][dt] *= alpha;
;         }
;         mL = full ? m_new * L2E : 1e30f;
;       } else {
;         mL = full ? st.m[hh] * L2E : 1e30f;
;         il = invl[hh];
;       }
;       float rs = 0.f;
; #pragma unroll
;       for (int kt = 0; kt < 4; ++kt) {
;         float a = 0.f;
; #pragma unroll
;         for (int j = 0; j < 4; ++j) {
;           float pv = __builtin_amdgcn_exp2f(fmaf(S[kt][hh][j], L2E, -mL));
;           if (MODE == 1) pv *= il;
;           S[kt][hh][j] = pv;
;           a += pv;
;         }
;     ...
;   if (MODE != 0) {
; #pragma unroll
;     for (int dt = 0; dt < 4; ++dt) {
;       const int row = dt * 16 + col;
;       const int sw = (row >> 1) & 7;
; #pragma unroll
;       for (int c = 0; c < 2; ++c) {
.Lnsa_fast:
	s_waitcnt lgkmcnt(7)
	v_mfma_f32_16x16x32_bf16 v[98:101], v[220:223], v[2:5], 0
	s_waitcnt lgkmcnt(6)
	v_mfma_f32_16x16x32_bf16 v[106:109], v[224:227], v[2:5], 0
	s_waitcnt lgkmcnt(5)
	v_mfma_f32_16x16x32_bf16 v[102:105], v[228:231], v[2:5], 0
	s_waitcnt lgkmcnt(4)
	v_mfma_f32_16x16x32_bf16 v[110:113], v[232:235], v[2:5], 0
	s_waitcnt lgkmcnt(3)
	v_mfma_f32_16x16x32_bf16 v[98:101], v[236:239], v[6:9], v[98:101]
	s_waitcnt lgkmcnt(2)
	v_mfma_f32_16x16x32_bf16 v[106:109], v[240:243], v[6:9], v[106:109]
	s_waitcnt lgkmcnt(1)
	v_mfma_f32_16x16x32_bf16 v[102:105], v[244:247], v[6:9], v[102:105]
	s_waitcnt lgkmcnt(0)
	v_mfma_f32_16x16x32_bf16 v[110:113], v[198:201], v[6:9], v[110:113]
	v_cmp_lt_i32_e32 vcc, 62, v215
	v_mfma_f32_16x16x32_bf16 v[90:93], v[220:223], v[10:13], 0
	v_mfma_f32_16x16x32_bf16 v[94:97], v[224:227], v[10:13], 0
	v_cndmask_b32_e32 v217, v197, v205, vcc
	v_mfma_f32_16x16x32_bf16 v[82:85], v[228:231], v[10:13], 0
	v_mfma_f32_16x16x32_bf16 v[86:89], v[232:235], v[10:13], 0
	v_fmamk_f32 v74, v98, 0x3fb8aa3b, v217
	v_fmamk_f32 v75, v99, 0x3fb8aa3b, v217
	v_mfma_f32_16x16x32_bf16 v[90:93], v[236:239], v[14:17], v[90:93]
	v_fmamk_f32 v76, v100, 0x3fb8aa3b, v217
	v_fmamk_f32 v77, v101, 0x3fb8aa3b, v217
	v_mfma_f32_16x16x32_bf16 v[94:97], v[240:243], v[14:17], v[94:97]
	v_fmamk_f32 v78, v106, 0x3fb8aa3b, v217
	v_fmamk_f32 v79, v107, 0x3fb8aa3b, v217
	v_mfma_f32_16x16x32_bf16 v[82:85], v[244:247], v[14:17], v[82:85]
	v_fmamk_f32 v80, v108, 0x3fb8aa3b, v217
	v_fmamk_f32 v81, v109, 0x3fb8aa3b, v217
	v_mfma_f32_16x16x32_bf16 v[86:89], v[198:201], v[14:17], v[86:89]
	ds_read_b64 v[220:221], v207 offset:8192
	v_fmamk_f32 v164, v102, 0x3fb8aa3b, v217
	ds_read_b64 v[222:223], v208 offset:8192
	v_fmamk_f32 v165, v103, 0x3fb8aa3b, v217
	ds_read_b64 v[224:225], v209 offset:8192
	v_fmamk_f32 v166, v104, 0x3fb8aa3b, v217
	ds_read_b64 v[226:227], v210 offset:8192
	v_fmamk_f32 v167, v105, 0x3fb8aa3b, v217
	ds_read_b64 v[228:229], v207 offset:10240
	v_fmamk_f32 v168, v110, 0x3fb8aa3b, v217
	ds_read_b64 v[230:231], v208 offset:10240
	v_fmamk_f32 v169, v111, 0x3fb8aa3b, v217
	ds_read_b64 v[232:233], v209 offset:10240
	v_fmamk_f32 v170, v112, 0x3fb8aa3b, v217
	ds_read_b64 v[234:235], v210 offset:10240
	v_fmamk_f32 v171, v113, 0x3fb8aa3b, v217
	ds_read_b64 v[236:237], v207 offset:12288
	v_exp_f32_e32 v74, v74
	ds_read_b64 v[238:239], v208 offset:12288
	v_exp_f32_e32 v75, v75
	ds_read_b64 v[240:241], v209 offset:12288
	v_exp_f32_e32 v76, v76
	ds_read_b64 v[242:243], v210 offset:12288
	v_exp_f32_e32 v77, v77
	ds_read_b64 v[244:245], v211 offset:8192
	v_exp_f32_e32 v78, v78
	ds_read_b64 v[246:247], v212 offset:8192
	v_exp_f32_e32 v79, v79
	ds_read_b64 v[198:199], v213 offset:8192
	v_exp_f32_e32 v80, v80
	ds_read_b64 v[200:201], v214 offset:8192
	v_exp_f32_e32 v81, v81
	v_exp_f32_e32 v164, v164
	v_exp_f32_e32 v165, v165
	v_exp_f32_e32 v166, v166
	v_exp_f32_e32 v167, v167
	v_exp_f32_e32 v168, v168
	v_exp_f32_e32 v169, v169
	v_exp_f32_e32 v170, v170
	v_exp_f32_e32 v171, v171
	v_cvt_pk_bf16_f32 v74, v74, v75
	v_cvt_pk_bf16_f32 v75, v76, v77
	v_cvt_pk_bf16_f32 v76, v78, v79
	v_cvt_pk_bf16_f32 v77, v80, v81
	v_cvt_pk_bf16_f32 v78, v164, v165
	v_cvt_pk_bf16_f32 v79, v166, v167
	v_cvt_pk_bf16_f32 v80, v168, v169
	v_cvt_pk_bf16_f32 v81, v170, v171
	s_waitcnt lgkmcnt(0)
	v_fmamk_f32 v164, v90, 0x3fb8aa3b, v217
	v_fmamk_f32 v165, v91, 0x3fb8aa3b, v217
	v_fmamk_f32 v166, v92, 0x3fb8aa3b, v217
	v_mfma_f32_16x16x32_bf16 v[50:53], v[220:223], v[74:77], v[50:53]
	v_fmamk_f32 v167, v93, 0x3fb8aa3b, v217
	s_mov_b32 s10, s8
	s_mov_b32 s11, s8
	s_mov_b32 s9, s8
	v_mfma_f32_16x16x32_bf16 v[42:45], v[228:231], v[74:77], v[42:45]
	v_mov_b64_e32 v[92:93], s[10:11]
	v_mov_b64_e32 v[90:91], s[8:9]
	v_fmamk_f32 v168, v94, 0x3fb8aa3b, v217
	v_fmamk_f32 v169, v95, 0x3fb8aa3b, v217
	v_mfma_f32_16x16x32_bf16 v[38:41], v[236:239], v[74:77], v[38:41]
	v_fmamk_f32 v170, v96, 0x3fb8aa3b, v217
	v_fmamk_f32 v171, v97, 0x3fb8aa3b, v217
	v_fmamk_f32 v172, v82, 0x3fb8aa3b, v217
	v_fmamk_f32 v173, v83, 0x3fb8aa3b, v217
	v_mfma_f32_16x16x32_bf16 v[34:37], v[244:247], v[74:77], v[34:37]
	v_fmamk_f32 v174, v84, 0x3fb8aa3b, v217
	v_fmamk_f32 v175, v85, 0x3fb8aa3b, v217
	v_fmamk_f32 v176, v86, 0x3fb8aa3b, v217
	v_fmamk_f32 v177, v87, 0x3fb8aa3b, v217
	v_mfma_f32_16x16x32_bf16 v[50:53], v[224:227], v[78:81], v[50:53]
	v_fmamk_f32 v178, v88, 0x3fb8aa3b, v217
	v_fmamk_f32 v179, v89, 0x3fb8aa3b, v217
	v_exp_f32_e32 v164, v164
	v_exp_f32_e32 v165, v165
	v_mfma_f32_16x16x32_bf16 v[42:45], v[232:235], v[78:81], v[42:45]
	v_exp_f32_e32 v166, v166
	v_exp_f32_e32 v167, v167
	v_exp_f32_e32 v168, v168
	v_exp_f32_e32 v169, v169
	v_mfma_f32_16x16x32_bf16 v[38:41], v[240:243], v[78:81], v[38:41]
	v_exp_f32_e32 v170, v170
	v_exp_f32_e32 v171, v171
	v_exp_f32_e32 v172, v172
	v_exp_f32_e32 v173, v173
	v_mfma_f32_16x16x32_bf16 v[34:37], v[198:201], v[78:81], v[34:37]
	v_exp_f32_e32 v174, v174
	v_exp_f32_e32 v175, v175
	v_exp_f32_e32 v176, v176
	v_exp_f32_e32 v177, v177
	v_mfma_f32_16x16x32_bf16 v[54:57], v[90:93], v[74:77], v[54:57]
	v_exp_f32_e32 v178, v178
	v_exp_f32_e32 v179, v179
	v_cvt_pk_bf16_f32 v82, v164, v165
	v_cvt_pk_bf16_f32 v83, v166, v167
	v_mfma_f32_16x16x32_bf16 v[54:57], v[90:93], v[78:81], v[54:57]
	v_cvt_pk_bf16_f32 v84, v168, v169
	v_cvt_pk_bf16_f32 v85, v170, v171
	v_cvt_pk_bf16_f32 v86, v172, v173
	v_cvt_pk_bf16_f32 v87, v174, v175
	v_cvt_pk_bf16_f32 v88, v176, v177
	v_cvt_pk_bf16_f32 v89, v178, v179
	s_nop 1
	v_mfma_f32_16x16x32_bf16 v[30:33], v[220:223], v[82:85], v[30:33]
	v_mfma_f32_16x16x32_bf16 v[26:29], v[228:231], v[82:85], v[26:29]
	v_mfma_f32_16x16x32_bf16 v[22:25], v[236:239], v[82:85], v[22:25]
	v_mfma_f32_16x16x32_bf16 v[18:21], v[244:247], v[82:85], v[18:21]
	v_mfma_f32_16x16x32_bf16 v[30:33], v[224:227], v[86:89], v[30:33]
	v_mfma_f32_16x16x32_bf16 v[26:29], v[232:235], v[86:89], v[26:29]
	v_mfma_f32_16x16x32_bf16 v[22:25], v[240:243], v[86:89], v[22:25]
	v_mfma_f32_16x16x32_bf16 v[18:21], v[198:201], v[86:89], v[18:21]
	v_mfma_f32_16x16x32_bf16 v[46:49], v[90:93], v[82:85], v[46:49]
	v_mfma_f32_16x16x32_bf16 v[46:49], v[90:93], v[86:89], v[46:49]
	s_branch .LBB0_667
; template <int MODE, bool FX>
; DI void attn_compute(const int lane, const bf16_t* Ks, const bf16_t* Vs, const bf16x8 (&qf)[2][2], AttnSt& st, const float (&invl)[2],
;                      int lo, int hi, float (&impA)[4], float (&impE)[4], const float CL) {
;     ...
;   for (int hh = 0; hh < 2; ++hh) {
;     if (FX) {
;       constexpr float L2E = 1.4426950408889634f;
;       const float il = (MODE == 1) ? invl[hh] : 1.f;
;       float rs = 0.f;
; #pragma unroll
;       for (int kt = 0; kt < 4; ++kt) {
;         float a = 0.f;
; #pragma unroll
;         for (int j = 0; j < 4; ++j) {
;           const int kl = kt * 16 + quad * 4 + j;
;           const bool v = (kl >= lo) && (kl <= hi);
;           float pv = v ? __builtin_amdgcn_exp2f(fmaf(S[kt][hh][j], L2E, -CL)) : 0.f;
;           if (MODE == 1) pv *= il;
;           S[kt][hh][j] = pv;
;           a += pv;
;         }
;         rs += a;
;         if (MODE == 1) {
;           impA[kt] += a;
;           impE[kt] += S[kt][hh][3];
;         }
;       }
;       if (MODE != 1 && !(FX && MODE == 2)) st.l[hh] += rs;
;       if (MODE != 0) {
; #pragma unroll
;         for (int c = 0; c < 2; ++c)
;           pf[hh][c] = mk8(pack2(S[2 * c][hh][0], S[2 * c][hh][1]), pack2(S[2 * c][hh][2], S[2 * c][hh][3]),
;                           pack2(S[2 * c + 1][hh][0], S[2 * c + 1][hh][1]), pack2(S[2 * c + 1][hh][2], S[2 * c + 1][hh][3]));
;       }
; template <bool FX>
; DI void nsa_tile(const Params& p, int b, int g, int tile, bf16_t* lds, const float CL) {
;     ...
;       for (int s = 0; s <= cur; ++s) {
;         __syncthreads();
;         tile64_sstore(tid, Ks, rk0, rk1);
;         tile64_sstore(tid, Vs, rv0, rv1);
;         __syncthreads();
;         if (s < cur) {
;           tile64_gload(tid, rk0, rk1, kb + (size_t)(s + 1) * 64 * ZS, ZS);
;           tile64_gload(tid, rv0, rv1, vsT + (s + 1) * 64, TS);
;         }
;         uint32_t wsel = (s < 32) ? sw0 : (s < 64) ? sw1 : (s < 96) ? sw2 : sw3;
;         bool sel = (wsel >> (s & 31)) & 1u;
;         int hi = sel ? (tok - s * 64) : -1;
;         if (__any(hi >= 0)) attn_compute<2, FX>(lane, Ks, Vs, qf, st, invl, 0, hi, dA, dE, CL);
;       }
.LBB0_667:
	s_add_i32 s28, s28, 64
	v_lshl_add_u64 v[160:161], v[160:161], 0, s[22:23]
	v_lshl_add_u64 v[158:159], v[158:159], 0, s[22:23]
	s_cmp_eq_u32 s25, s68
	v_subrev_u32_e32 v187, 64, v187
	s_cbranch_scc1 .LBB0_675
.LBB0_668:
	s_add_i32 s68, s68, 1
	s_cmp_ge_u32 s68, s25
	s_barrier
	s_waitcnt vmcnt(3)
	ds_write_b128 v163, v[58:61]
	s_waitcnt vmcnt(2)
	ds_write_b128 v163, v[62:65] offset:4096
	s_waitcnt vmcnt(1)
	ds_write_b128 v163, v[66:69] offset:8192
	s_waitcnt vmcnt(0)
	ds_write_b128 v163, v[70:73] offset:12288
	s_waitcnt lgkmcnt(0)
	s_barrier
	s_cbranch_scc1 .LBB0_670
	s_lshl_b64 s[2:3], s[28:29], 1
	s_add_u32 s2, s12, s2
	s_addc_u32 s3, s13, s3
	v_lshl_add_u64 v[66:67], v[138:139], 1, s[2:3]
	v_lshl_add_u64 v[68:69], v[142:143], 1, s[2:3]
	v_lshl_add_u64 v[66:67], v[66:67], 0, v[0:1]
	v_lshl_add_u64 v[70:71], v[68:69], 0, v[0:1]
	global_load_dwordx4 v[58:61], v[158:159], off
	global_load_dwordx4 v[62:65], v[160:161], off
	s_nop 0
	global_load_dwordx4 v[66:69], v[66:67], off
	s_nop 0
	global_load_dwordx4 v[70:73], v[70:71], off
.LBB0_670:
	s_cmp_lt_u32 s68, 32
	s_cselect_b64 vcc, -1, 0
	s_cmp_lt_u32 s68, 64
	s_cselect_b64 s[2:3], -1, 0
	s_cmpk_lt_u32 s68, 0x60
	s_cselect_b64 s[4:5], -1, 0
	v_cndmask_b32_e64 v74, v183, v182, s[4:5]
	v_cndmask_b32_e64 v74, v74, v181, s[2:3]
	v_cndmask_b32_e32 v74, v74, v180, vcc
	v_lshrrev_b32_e32 v74, s68, v74
	v_and_b32_e32 v74, 1, v74
	v_cmp_eq_u32_e32 vcc, 1, v74
	s_nop 1
	v_cndmask_b32_e32 v215, -1, v187, vcc
	v_cmp_lt_i32_e32 vcc, -1, v215
	s_cbranch_vccz .LBB0_667
	ds_read_b128 v[220:223], v188
	ds_read_b128 v[224:227], v188 offset:2048
	ds_read_b128 v[228:231], v188 offset:4096
	ds_read_b128 v[232:235], v189
	ds_read_b128 v[236:239], v190
	ds_read_b128 v[240:243], v190 offset:2048
	ds_read_b128 v[244:247], v190 offset:4096
	ds_read_b128 v[198:201], v191
	v_cmp_lt_u32_e32 vcc, 62, v215
	s_mov_b64 s[2:3], -1
	s_cmp_eq_u64 vcc, exec
	s_cbranch_scc1 .Lnsa_fast
.Lnsa_masked:
	v_cmp_gt_i32_e32 vcc, v118, v215
	v_cmp_lt_i32_e64 s[2:3], v118, v215
	v_cmp_gt_i32_e64 s[52:53], v119, v215
	v_cmp_gt_i32_e64 s[54:55], v192, v215
	v_cmp_gt_i32_e64 s[40:41], v120, v215
	v_cmp_gt_i32_e64 s[42:43], v193, v215
	v_cmp_gt_i32_e64 s[56:57], v122, v215
	v_cmp_gt_i32_e64 s[58:59], v121, v215
	v_cmp_gt_i32_e64 s[44:45], v194, v215
	v_cmp_gt_i32_e64 s[46:47], v195, v215
	v_cmp_gt_i32_e64 s[60:61], v206, v215
	v_cmp_gt_i32_e64 s[62:63], v124, v215
	v_cmp_gt_i32_e64 s[48:49], v126, v215
	v_cmp_gt_i32_e64 s[50:51], v123, v215
	v_cmp_gt_i32_e64 s[64:65], v125, v215
	v_cmp_gt_i32_e64 s[66:67], v127, v215
	s_waitcnt lgkmcnt(7)
	v_mfma_f32_16x16x32_bf16 v[98:101], v[220:223], v[2:5], 0
	s_waitcnt lgkmcnt(6)
	v_mfma_f32_16x16x32_bf16 v[106:109], v[224:227], v[2:5], 0
	s_waitcnt lgkmcnt(5)
	v_mfma_f32_16x16x32_bf16 v[102:105], v[228:231], v[2:5], 0
	s_waitcnt lgkmcnt(4)
	v_mfma_f32_16x16x32_bf16 v[110:113], v[232:235], v[2:5], 0
	s_waitcnt lgkmcnt(3)
	v_mfma_f32_16x16x32_bf16 v[98:101], v[236:239], v[6:9], v[98:101]
	s_waitcnt lgkmcnt(2)
	v_mfma_f32_16x16x32_bf16 v[106:109], v[240:243], v[6:9], v[106:109]
	s_waitcnt lgkmcnt(1)
	v_mfma_f32_16x16x32_bf16 v[102:105], v[244:247], v[6:9], v[102:105]
	s_waitcnt lgkmcnt(0)
	v_mfma_f32_16x16x32_bf16 v[110:113], v[198:201], v[6:9], v[110:113]
	v_mfma_f32_16x16x32_bf16 v[90:93], v[220:223], v[10:13], 0
	v_mfma_f32_16x16x32_bf16 v[94:97], v[224:227], v[10:13], 0
	v_mfma_f32_16x16x32_bf16 v[82:85], v[228:231], v[10:13], 0
	v_mfma_f32_16x16x32_bf16 v[86:89], v[232:235], v[10:13], 0
	v_fmamk_f32 v74, v98, 0x3fb8aa3b, v205
	v_fmamk_f32 v75, v99, 0x3fb8aa3b, v205
	v_mfma_f32_16x16x32_bf16 v[90:93], v[236:239], v[14:17], v[90:93]
	v_fmamk_f32 v76, v100, 0x3fb8aa3b, v205
	v_fmamk_f32 v77, v101, 0x3fb8aa3b, v205
	v_mfma_f32_16x16x32_bf16 v[94:97], v[240:243], v[14:17], v[94:97]
	v_fmamk_f32 v78, v106, 0x3fb8aa3b, v205
	v_fmamk_f32 v79, v107, 0x3fb8aa3b, v205
	v_mfma_f32_16x16x32_bf16 v[82:85], v[244:247], v[14:17], v[82:85]
	v_fmamk_f32 v80, v108, 0x3fb8aa3b, v205
	v_fmamk_f32 v81, v109, 0x3fb8aa3b, v205
	v_mfma_f32_16x16x32_bf16 v[86:89], v[198:201], v[14:17], v[86:89]
	ds_read_b64 v[220:221], v207 offset:8192
	v_fmamk_f32 v164, v102, 0x3fb8aa3b, v205
	ds_read_b64 v[222:223], v208 offset:8192
	v_fmamk_f32 v165, v103, 0x3fb8aa3b, v205
	ds_read_b64 v[224:225], v209 offset:8192
	v_fmamk_f32 v166, v104, 0x3fb8aa3b, v205
	ds_read_b64 v[226:227], v210 offset:8192
	v_fmamk_f32 v167, v105, 0x3fb8aa3b, v205
	ds_read_b64 v[228:229], v207 offset:10240
	v_fmamk_f32 v168, v110, 0x3fb8aa3b, v205
	ds_read_b64 v[230:231], v208 offset:10240
	v_fmamk_f32 v169, v111, 0x3fb8aa3b, v205
	ds_read_b64 v[232:233], v209 offset:10240
	v_fmamk_f32 v170, v112, 0x3fb8aa3b, v205
	ds_read_b64 v[234:235], v210 offset:10240
	v_fmamk_f32 v171, v113, 0x3fb8aa3b, v205
	ds_read_b64 v[236:237], v207 offset:12288
	v_exp_f32_e32 v74, v74
	ds_read_b64 v[238:239], v208 offset:12288
	v_exp_f32_e32 v75, v75
	ds_read_b64 v[240:241], v209 offset:12288
	v_exp_f32_e32 v76, v76
	ds_read_b64 v[242:243], v210 offset:12288
	v_exp_f32_e32 v77, v77
	ds_read_b64 v[244:245], v211 offset:8192
	v_exp_f32_e32 v78, v78
	ds_read_b64 v[246:247], v212 offset:8192
	v_exp_f32_e32 v79, v79
	ds_read_b64 v[198:199], v213 offset:8192
	v_exp_f32_e32 v80, v80
	ds_read_b64 v[200:201], v214 offset:8192
	v_exp_f32_e32 v81, v81
	v_exp_f32_e32 v164, v164
	v_exp_f32_e32 v165, v165
	v_exp_f32_e32 v166, v166
	v_exp_f32_e32 v167, v167
	v_exp_f32_e32 v168, v168
	v_exp_f32_e32 v169, v169
	v_exp_f32_e32 v170, v170
	v_exp_f32_e32 v171, v171
	v_cndmask_b32_e64 v74, v74, 0, vcc
	v_cndmask_b32_e64 v75, 0, v75, s[2:3]
	v_cndmask_b32_e64 v76, v76, 0, s[52:53]
	v_cndmask_b32_e64 v77, v77, 0, s[54:55]
	v_cndmask_b32_e64 v78, v78, 0, s[40:41]
	v_cndmask_b32_e64 v79, v79, 0, s[42:43]
	v_cndmask_b32_e64 v80, v80, 0, s[56:57]
	v_cndmask_b32_e64 v81, v81, 0, s[58:59]
	v_cndmask_b32_e64 v164, v164, 0, s[44:45]
	v_cndmask_b32_e64 v165, v165, 0, s[46:47]
	v_cndmask_b32_e64 v166, v166, 0, s[60:61]
	v_cndmask_b32_e64 v167, v167, 0, s[62:63]
	v_cndmask_b32_e64 v168, v168, 0, s[48:49]
	v_cndmask_b32_e64 v169, v169, 0, s[50:51]
	v_cndmask_b32_e64 v170, v170, 0, s[64:65]
	v_cndmask_b32_e64 v171, v171, 0, s[66:67]
	v_cvt_pk_bf16_f32 v74, v74, v75
	v_cvt_pk_bf16_f32 v75, v76, v77
	v_cvt_pk_bf16_f32 v76, v78, v79
	v_cvt_pk_bf16_f32 v77, v80, v81
	v_cvt_pk_bf16_f32 v78, v164, v165
	v_cvt_pk_bf16_f32 v79, v166, v167
	v_cvt_pk_bf16_f32 v80, v168, v169
	v_cvt_pk_bf16_f32 v81, v170, v171
	s_waitcnt lgkmcnt(0)
; DI f32x4 mfma16(bf16x8 a, bf16x8 b, f32x4 c) { return __builtin_amdgcn_mfma_f32_16x16x32_bf16(a, b, c, 0, 0, 0); }
; template <int MODE, bool FX>
; DI void attn_compute(const int lane, const bf16_t* Ks, const bf16_t* Vs, const bf16x8 (&qf)[2][2], AttnSt& st, const float (&invl)[2],
;                      int lo, int hi, float (&impA)[4], float (&impE)[4], const float CL) {
;     ...
;       for (int kt = 0; kt < 4; ++kt) {
;         float a = 0.f;
; #pragma unroll
;         for (int j = 0; j < 4; ++j) {
;           const int kl = kt * 16 + quad * 4 + j;
;           const bool v = (kl >= lo) && (kl <= hi);
;           float pv = v ? __builtin_amdgcn_exp2f(fmaf(S[kt][hh][j], L2E, -CL)) : 0.f;
;           if (MODE == 1) pv *= il;
;           S[kt][hh][j] = pv;
;           a += pv;
;         }
;         rs += a;
;         if (MODE == 1) {
;           impA[kt] += a;
;           impE[kt] += S[kt][hh][3];
;         }
;       }
;       if (MODE != 1 && !(FX && MODE == 2)) st.l[hh] += rs;
;       if (MODE != 0) {
; #pragma unroll
;         for (int c = 0; c < 2; ++c)
;           pf[hh][c] = mk8(pack2(S[2 * c][hh][0], S[2 * c][hh][1]), pack2(S[2 * c][hh][2], S[2 * c][hh][3]),
;                           pack2(S[2 * c + 1][hh][0], S[2 * c + 1][hh][1]), pack2(S[2 * c + 1][hh][2], S[2 * c + 1][hh][3]));
;       }
;     ...
;   if (MODE != 0) {
; #pragma unroll
;     for (int dt = 0; dt < 4; ++dt) {
;       const int row = dt * 16 + col;
;       const int sw = (row >> 1) & 7;
; #pragma unroll
;       for (int c = 0; c < 2; ++c) {
;         uint2 a = *(const uint2*)(Vs + row * 64 + (((4 * c + (quad >> 1)) ^ sw) << 3) + (quad & 1) * 4);
;         uint2 b = *(const uint2*)(Vs + row * 64 + (((4 * c + 2 + (quad >> 1)) ^ sw) << 3) + (quad & 1) * 4);
;         bf16x8 vf = mk8(a.x, a.y, b.x, b.y);
; #pragma unroll
;         for (int hh = 0; hh < 2; ++hh) st.O[hh][dt] = mfma16(vf, pf[hh][c], st.O[hh][dt]);
;       }
;     }
;     if (FX && MODE == 2) {
;       const bf16x8 ones = mk8(0x3F803F80u, 0x3F803F80u, 0x3F803F80u, 0x3F803F80u);
; #pragma unroll
;       for (int c = 0; c < 2; ++c)
; #pragma unroll
;         for (int hh = 0; hh < 2; ++hh) st.L[hh] = mfma16(ones, pf[hh][c], st.L[hh]);
;     }
	v_fmamk_f32 v164, v90, 0x3fb8aa3b, v205
	v_fmamk_f32 v165, v91, 0x3fb8aa3b, v205
	v_fmamk_f32 v166, v92, 0x3fb8aa3b, v205
	v_mfma_f32_16x16x32_bf16 v[50:53], v[220:223], v[74:77], v[50:53]
	v_fmamk_f32 v167, v93, 0x3fb8aa3b, v205
	s_mov_b32 s10, s8
	s_mov_b32 s11, s8
	s_mov_b32 s9, s8
	v_mov_b64_e32 v[92:93], s[10:11]
	v_mfma_f32_16x16x32_bf16 v[42:45], v[228:231], v[74:77], v[42:45]
	v_mov_b64_e32 v[90:91], s[8:9]
	v_fmamk_f32 v168, v94, 0x3fb8aa3b, v205
	v_fmamk_f32 v169, v95, 0x3fb8aa3b, v205
	v_fmamk_f32 v170, v96, 0x3fb8aa3b, v205
	v_fmamk_f32 v171, v97, 0x3fb8aa3b, v205
	v_mfma_f32_16x16x32_bf16 v[38:41], v[236:239], v[74:77], v[38:41]
	v_fmamk_f32 v172, v82, 0x3fb8aa3b, v205
	v_fmamk_f32 v173, v83, 0x3fb8aa3b, v205
	v_fmamk_f32 v174, v84, 0x3fb8aa3b, v205
	v_fmamk_f32 v175, v85, 0x3fb8aa3b, v205
	v_fmamk_f32 v176, v86, 0x3fb8aa3b, v205
	v_mfma_f32_16x16x32_bf16 v[34:37], v[244:247], v[74:77], v[34:37]
	v_fmamk_f32 v177, v87, 0x3fb8aa3b, v205
	v_fmamk_f32 v178, v88, 0x3fb8aa3b, v205
	v_fmamk_f32 v179, v89, 0x3fb8aa3b, v205
	v_exp_f32_e32 v164, v164
	v_exp_f32_e32 v165, v165
	v_mfma_f32_16x16x32_bf16 v[50:53], v[224:227], v[78:81], v[50:53]
	v_exp_f32_e32 v166, v166
	v_exp_f32_e32 v167, v167
	v_exp_f32_e32 v168, v168
	v_exp_f32_e32 v169, v169
	v_exp_f32_e32 v170, v170
	v_mfma_f32_16x16x32_bf16 v[42:45], v[232:235], v[78:81], v[42:45]
	v_exp_f32_e32 v171, v171
	v_exp_f32_e32 v172, v172
	v_exp_f32_e32 v173, v173
	v_exp_f32_e32 v174, v174
	v_exp_f32_e32 v175, v175
	v_mfma_f32_16x16x32_bf16 v[38:41], v[240:243], v[78:81], v[38:41]
	v_exp_f32_e32 v176, v176
	v_exp_f32_e32 v177, v177
	v_exp_f32_e32 v178, v178
	v_exp_f32_e32 v179, v179
	v_cndmask_b32_e64 v164, v164, 0, vcc
	v_mfma_f32_16x16x32_bf16 v[34:37], v[198:201], v[78:81], v[34:37]
	v_cndmask_b32_e64 v165, 0, v165, s[2:3]
	v_cndmask_b32_e64 v166, v166, 0, s[52:53]
	v_cndmask_b32_e64 v167, v167, 0, s[54:55]
	v_cndmask_b32_e64 v168, v168, 0, s[40:41]
	v_cndmask_b32_e64 v169, v169, 0, s[42:43]
	v_mfma_f32_16x16x32_bf16 v[54:57], v[90:93], v[74:77], v[54:57]
	v_cndmask_b32_e64 v170, v170, 0, s[56:57]
	v_cndmask_b32_e64 v171, v171, 0, s[58:59]
	v_cndmask_b32_e64 v172, v172, 0, s[44:45]
	v_cndmask_b32_e64 v173, v173, 0, s[46:47]
	v_cndmask_b32_e64 v174, v174, 0, s[60:61]
	v_mfma_f32_16x16x32_bf16 v[54:57], v[90:93], v[78:81], v[54:57]
	v_cndmask_b32_e64 v175, v175, 0, s[62:63]
	v_cndmask_b32_e64 v176, v176, 0, s[48:49]
	v_cndmask_b32_e64 v177, v177, 0, s[50:51]
	v_cndmask_b32_e64 v178, v178, 0, s[64:65]
	v_cndmask_b32_e64 v179, v179, 0, s[66:67]
	v_cvt_pk_bf16_f32 v82, v164, v165
	v_cvt_pk_bf16_f32 v83, v166, v167
	v_cvt_pk_bf16_f32 v84, v168, v169
	v_cvt_pk_bf16_f32 v85, v170, v171
	v_cvt_pk_bf16_f32 v86, v172, v173
	v_cvt_pk_bf16_f32 v87, v174, v175
	v_cvt_pk_bf16_f32 v88, v176, v177
	v_cvt_pk_bf16_f32 v89, v178, v179
	s_nop 1
	v_mfma_f32_16x16x32_bf16 v[30:33], v[220:223], v[82:85], v[30:33]
	v_mfma_f32_16x16x32_bf16 v[26:29], v[228:231], v[82:85], v[26:29]
	v_mfma_f32_16x16x32_bf16 v[22:25], v[236:239], v[82:85], v[22:25]
	v_mfma_f32_16x16x32_bf16 v[18:21], v[244:247], v[82:85], v[18:21]
	v_mfma_f32_16x16x32_bf16 v[30:33], v[224:227], v[86:89], v[30:33]
	v_mfma_f32_16x16x32_bf16 v[26:29], v[232:235], v[86:89], v[26:29]
	v_mfma_f32_16x16x32_bf16 v[22:25], v[240:243], v[86:89], v[22:25]
	v_mfma_f32_16x16x32_bf16 v[18:21], v[198:201], v[86:89], v[18:21]
	v_mfma_f32_16x16x32_bf16 v[46:49], v[90:93], v[82:85], v[46:49]
	v_mfma_f32_16x16x32_bf16 v[46:49], v[90:93], v[86:89], v[46:49]
	s_branch .LBB0_667
